# main LayerNorm loop software-prefetches the next iteration's rows (one iteration of loads in flight, stores never waited for)
# baseline (speedup 1.0000x reference)
.LBB0_1429:
	s_or_b64 exec, exec, s[0:1]
	v_readlane_b32 s4, v254, 37
	v_readlane_b32 s5, v254, 38
	s_mov_b64 s[0:1], -1
	s_and_b64 vcc, exec, s[4:5]
	s_waitcnt lgkmcnt(0)
	s_barrier
	s_cbranch_vccz .LBB0_1443
	v_mov_b32_e32 v0, v224
	v_readlane_b32 s1, v254, 41
	v_readfirstlane_b32 s0, v0
	s_ashr_i32 s0, s0, 6
	s_add_i32 s0, s1, s0
	s_cmp_gt_i32 s0, 0xffff
	s_cbranch_scc1 .LBB0_1442
	s_lshl_b32 s4, s19, 10
	s_mov_b32 s5, s68
	s_lshl_b64 s[4:5], s[4:5], 2
	s_add_u32 s6, s54, s4
	s_addc_u32 s7, s55, s5
	v_lshlrev_b32_e32 v0, 3, v0
	s_add_u32 s4, s52, s4
	s_waitcnt vmcnt(1)
	v_and_b32_e32 v34, 0x1f8, v0
	s_addc_u32 s5, s53, s5
	v_lshlrev_b32_e32 v0, 2, v34
	global_load_dwordx4 v[2:5], v0, s[4:5] offset:16
	global_load_dwordx4 v[6:9], v0, s[4:5]
	global_load_dwordx4 v[10:13], v0, s[6:7] offset:16
	global_load_dwordx4 v[14:17], v0, s[6:7]
	global_load_dwordx4 v[18:21], v0, s[4:5] offset:2064
	global_load_dwordx4 v[22:25], v0, s[4:5] offset:2048
	global_load_dwordx4 v[26:29], v0, s[6:7] offset:2064
	global_load_dwordx4 v[30:33], v0, s[6:7] offset:2048
	v_readlane_b32 s4, v254, 42
	v_lshlrev_b32_e32 v34, 1, v34
	v_mov_b32_e32 v35, v1
	v_readlane_b32 s5, v254, 43
	s_waitcnt vmcnt(8)
	v_lshl_add_u64 v[58:59], s[28:29], 0, v[34:35]
	v_lshl_add_u64 v[62:63], s[56:57], 0, v[0:1]
	v_lshl_add_u64 v[60:61], s[4:5], 0, v[34:35]
	v_and_b32_e32 v34, 64, v229
	v_add_u32_e32 v34, 64, v34
	v_xor_b32_e32 v35, 1, v229
	v_cmp_lt_i32_e32 vcc, v35, v34
	s_nop 1
	v_cndmask_b32_e32 v35, v229, v35, vcc
	v_lshlrev_b32_e32 v68, 2, v35
	v_xor_b32_e32 v35, 2, v229
	v_cmp_lt_i32_e32 vcc, v35, v34
	s_nop 1
	v_cndmask_b32_e32 v35, v229, v35, vcc
	v_lshlrev_b32_e32 v69, 2, v35
	v_xor_b32_e32 v35, 4, v229
	v_cmp_lt_i32_e32 vcc, v35, v34
	s_nop 1
	v_cndmask_b32_e32 v35, v229, v35, vcc
	v_lshlrev_b32_e32 v70, 2, v35
	v_xor_b32_e32 v35, 8, v229
	v_cmp_lt_i32_e32 vcc, v35, v34
	s_nop 1
	v_cndmask_b32_e32 v35, v229, v35, vcc
	v_lshlrev_b32_e32 v71, 2, v35
	v_xor_b32_e32 v35, 16, v229
	v_cmp_lt_i32_e32 vcc, v35, v34
	s_nop 1
	v_cndmask_b32_e32 v35, v229, v35, vcc
	v_lshlrev_b32_e32 v72, 2, v35
	v_xor_b32_e32 v35, 32, v229
	v_cmp_lt_i32_e32 vcc, v35, v34
	s_nop 1
	v_cndmask_b32_e32 v34, v229, v35, vcc
	v_lshlrev_b32_e32 v73, 2, v34
	s_mov_b32 s100, s0
	v_readlane_b32 vcc_lo, v254, 39
	s_add_i32 vcc_lo, vcc_lo, s100
	s_sub_i32 vcc_lo, vcc_lo, 32
	s_cmp_lt_i32 vcc_lo, 0x10000
	s_cselect_b32 vcc_lo, vcc_lo, s100
	s_xor_b32 s100, s100, 0xffff
	s_xor_b32 vcc_lo, vcc_lo, 0xffff
	s_lshl_b32 s100, s100, 11
	s_lshl_b32 vcc_lo, vcc_lo, 11
	v_mov_b32_e32 v114, s100
	v_mov_b32_e32 v115, v1
	v_mov_b32_e32 v116, vcc_lo
	v_mov_b32_e32 v117, v1
	v_lshl_add_u64 v[114:115], v[58:59], 0, v[114:115]
	v_lshl_add_u64 v[116:117], v[58:59], 0, v[116:117]
	global_load_dwordx4 v[98:101], v[114:115], off
	global_load_dwordx4 v[102:105], v[114:115], off offset:1024
	global_load_dwordx4 v[106:109], v[116:117], off
	global_load_dwordx4 v[110:113], v[116:117], off offset:1024
	s_waitcnt vmcnt(0)
	s_branch .LBB0_1433

.LBB0_1433:
	v_readlane_b32 s1, v254, 39
	s_add_i32 s1, s1, s0
	s_sub_i32 s4, s1, 32
	s_ashr_i32 s1, s0, 31
	s_xor_b32 s8, s0, 0xffff
	s_mov_b32 s9, 0
	s_lshl_b64 s[8:9], s[8:9], 11
	s_cmp_lt_i32 s4, 0x10000
	s_cselect_b64 s[6:7], -1, 0
	s_and_b64 s[10:11], s[6:7], exec
	s_cselect_b32 s10, s4, s0
	s_ashr_i32 s11, s10, 31
	s_xor_b32 s10, s10, 0xffff
	s_lshl_b64 s[10:11], s[10:11], 11
	s_waitcnt vmcnt(4)
	v_mov_b32_e32 v50, v98
	v_mov_b32_e32 v51, v99
	v_mov_b32_e32 v52, v100
	v_mov_b32_e32 v53, v101
	v_mov_b32_e32 v44, v102
	v_mov_b32_e32 v45, v103
	v_mov_b32_e32 v46, v104
	v_mov_b32_e32 v47, v105
	v_mov_b32_e32 v34, v106
	v_mov_b32_e32 v35, v107
	v_mov_b32_e32 v36, v108
	v_mov_b32_e32 v37, v109
	v_mov_b32_e32 v38, v110
	v_mov_b32_e32 v39, v111
	v_mov_b32_e32 v40, v112
	v_mov_b32_e32 v41, v113
	v_readlane_b32 s100, v254, 40
	s_lshl_b32 s100, s100, 1
	s_add_i32 s100, s100, s0
	s_cmp_lt_i32 s100, 0x10000
	s_cselect_b32 s100, s100, s0
	v_readlane_b32 vcc_lo, v254, 39
	s_add_i32 vcc_lo, vcc_lo, s100
	s_sub_i32 vcc_lo, vcc_lo, 32
	s_cmp_lt_i32 vcc_lo, 0x10000
	s_cselect_b32 vcc_lo, vcc_lo, s100
	s_xor_b32 s100, s100, 0xffff
	s_xor_b32 vcc_lo, vcc_lo, 0xffff
	s_lshl_b32 s100, s100, 11
	s_lshl_b32 vcc_lo, vcc_lo, 11
	v_mov_b32_e32 v114, s100
	v_mov_b32_e32 v115, v1
	v_mov_b32_e32 v116, vcc_lo
	v_mov_b32_e32 v117, v1
	v_lshl_add_u64 v[114:115], v[58:59], 0, v[114:115]
	v_lshl_add_u64 v[116:117], v[58:59], 0, v[116:117]
	global_load_dwordx4 v[98:101], v[114:115], off
	global_load_dwordx4 v[102:105], v[114:115], off offset:1024
	global_load_dwordx4 v[106:109], v[116:117], off
	global_load_dwordx4 v[110:113], v[116:117], off offset:1024
	s_mov_b64 s[10:11], -1
	v_and_b32_e32 v75, 0xffff0000, v51
	v_lshlrev_b32_e32 v56, 16, v46
	v_and_b32_e32 v66, 0xffff0000, v46
	v_lshlrev_b32_e32 v54, 16, v47
	v_and_b32_e32 v64, 0xffff0000, v47
	v_lshlrev_b32_e32 v47, 16, v51
	v_lshlrev_b32_e32 v46, 16, v50
	v_and_b32_e32 v74, 0xffff0000, v50
	v_pk_add_f32 v[48:49], v[46:47], v[74:75]
	v_lshlrev_b32_e32 v51, 16, v53
	v_lshlrev_b32_e32 v50, 16, v52
	v_and_b32_e32 v77, 0xffff0000, v53
	v_and_b32_e32 v76, 0xffff0000, v52
	v_add_f32_e32 v0, v48, v49
	v_pk_add_f32 v[48:49], v[50:51], v[76:77]
	v_lshlrev_b32_e32 v42, 16, v44
	v_and_b32_e32 v43, 0xffff0000, v44
	v_lshlrev_b32_e32 v44, 16, v45
	v_and_b32_e32 v45, 0xffff0000, v45
	v_pk_add_f32 v[48:49], v[48:49], v[48:49] op_sel_hi:[0,1]
	v_add_f32_e32 v65, 0, v0
	v_add_f32_e32 v57, v42, v43
	v_add_f32_e32 v67, v44, v45
	v_mov_b32_e32 v55, v49
	v_pk_add_f32 v[52:53], v[56:57], v[66:67]
	v_pk_add_f32 v[48:49], v[54:55], v[64:65]
	s_nop 0
	v_pk_add_f32 v[48:49], v[52:53], v[48:49]
	s_nop 0
	v_add_f32_e32 v0, v48, v49
	ds_bpermute_b32 v48, v68, v0
	s_waitcnt lgkmcnt(0)
	v_add_f32_e32 v0, v0, v48
	ds_bpermute_b32 v48, v69, v0
	s_waitcnt lgkmcnt(0)
	v_add_f32_e32 v0, v0, v48
	ds_bpermute_b32 v48, v70, v0
	s_waitcnt lgkmcnt(0)
	v_add_f32_e32 v0, v0, v48
	ds_bpermute_b32 v48, v71, v0
	s_waitcnt lgkmcnt(0)
	v_add_f32_e32 v0, v0, v48
	ds_bpermute_b32 v48, v72, v0
	s_waitcnt lgkmcnt(0)
	v_add_f32_e32 v0, v0, v48
	ds_bpermute_b32 v48, v73, v0
	s_waitcnt lgkmcnt(0)
	v_add_f32_e32 v55, v0, v48
	v_fmac_f32_e32 v74, 0xba800000, v55
	v_fmac_f32_e32 v75, 0xba800000, v55
	v_fmac_f32_e32 v47, 0xba800000, v55
	v_fmac_f32_e32 v46, 0xba800000, v55
	v_mov_b32_e32 v48, v47
	v_mov_b32_e32 v49, v75
	v_mov_b32_e32 v47, v74
	v_pk_mul_f32 v[52:53], v[48:49], v[48:49]
	v_pk_mul_f32 v[74:75], v[46:47], v[46:47]
	v_fmac_f32_e32 v76, 0xba800000, v55
	v_pk_mov_b32 v[78:79], v[74:75], v[52:53] op_sel:[1,0]
	v_mov_b32_e32 v75, v53
	v_fmac_f32_e32 v77, 0xba800000, v55
	v_fmac_f32_e32 v51, 0xba800000, v55
	v_pk_add_f32 v[52:53], v[78:79], v[74:75]
	v_fmac_f32_e32 v50, 0xba800000, v55
	v_mov_b32_e32 v74, v51
	v_mov_b32_e32 v75, v77
	v_mov_b32_e32 v51, v76
	v_pk_mul_f32 v[78:79], v[74:75], v[74:75]
	v_pk_mul_f32 v[76:77], v[50:51], v[50:51]
	v_fmac_f32_e32 v42, 0xba800000, v55
	v_pk_mov_b32 v[80:81], v[76:77], v[78:79] op_sel:[1,0]
	v_mov_b32_e32 v77, v79
	v_fmac_f32_e32 v43, 0xba800000, v55
	v_fmac_f32_e32 v44, 0xba800000, v55
	v_mul_f32_e32 v0, v42, v42
	v_pk_add_f32 v[76:77], v[80:81], v[76:77]
	v_fmac_f32_e32 v45, 0xba800000, v55
	v_pk_fma_f32 v[78:79], v[42:43], v[42:43], v[0:1] op_sel_hi:[1,1,0]
	v_mul_f32_e32 v0, v44, v44
	v_pk_add_f32 v[52:53], v[52:53], v[52:53] op_sel_hi:[0,1]
	v_pk_add_f32 v[76:77], v[76:77], v[76:77] op_sel_hi:[0,1]
	v_pk_fma_f32 v[80:81], v[44:45], v[44:45], v[0:1] op_sel_hi:[1,1,0]
	v_fmac_f32_e32 v64, 0xba800000, v55
	v_fmac_f32_e32 v54, 0xba800000, v55
	v_fmac_f32_e32 v66, 0xba800000, v55
	v_fmac_f32_e32 v56, 0xba800000, v55
	v_mul_f32_e32 v78, v56, v56
	v_mul_f32_e32 v80, v66, v66
	v_mul_f32_e32 v52, v54, v54
	v_mul_f32_e32 v76, v64, v64
	v_pk_add_f32 v[78:79], v[78:79], v[80:81]
	v_pk_add_f32 v[52:53], v[52:53], v[76:77]
	v_mov_b32_e32 v57, v66
	v_pk_add_f32 v[52:53], v[78:79], v[52:53]
	v_mov_b32_e32 v55, v64
	v_add_f32_e32 v0, v52, v53
	ds_bpermute_b32 v52, v68, v0
	s_waitcnt lgkmcnt(0)
	v_add_f32_e32 v0, v0, v52
	ds_bpermute_b32 v52, v69, v0
	s_waitcnt lgkmcnt(0)
	v_add_f32_e32 v0, v0, v52
	ds_bpermute_b32 v52, v70, v0
	s_waitcnt lgkmcnt(0)
	v_add_f32_e32 v0, v0, v52
	ds_bpermute_b32 v52, v71, v0
	s_waitcnt lgkmcnt(0)
	v_add_f32_e32 v0, v0, v52
	ds_bpermute_b32 v52, v72, v0
	s_waitcnt lgkmcnt(0)
	v_add_f32_e32 v0, v0, v52
	ds_bpermute_b32 v52, v73, v0
	s_waitcnt lgkmcnt(0)
	v_add_f32_e32 v0, v0, v52
	v_fmamk_f32 v0, v0, 0x3a800000, v227
	v_cmp_gt_f32_e32 vcc, s86, v0
	v_mul_f32_e32 v52, 0x4b800000, v0
	s_nop 0
	v_cndmask_b32_e32 v0, v0, v52, vcc
	v_rsq_f32_e32 v0, v0
	s_nop 0
	v_mul_f32_e32 v52, 0x45800000, v0
	v_cndmask_b32_e32 v0, v0, v52, vcc
	v_pk_mul_f32 v[46:47], v[46:47], v[0:1] op_sel_hi:[1,0]
	v_pk_mul_f32 v[48:49], v[48:49], v[0:1] op_sel_hi:[1,0]
	v_pk_mul_f32 v[50:51], v[50:51], v[0:1] op_sel_hi:[1,0]
	v_pk_mul_f32 v[52:53], v[74:75], v[0:1] op_sel_hi:[1,0]
	v_pk_mul_f32 v[42:43], v[42:43], v[0:1] op_sel_hi:[1,0]
	v_pk_mul_f32 v[44:45], v[44:45], v[0:1] op_sel_hi:[1,0]
	v_pk_mul_f32 v[66:67], v[56:57], v[0:1] op_sel_hi:[1,0]
	v_pk_mul_f32 v[54:55], v[54:55], v[0:1] op_sel_hi:[1,0]
	v_pk_fma_f32 v[48:49], v[8:9], v[48:49], v[16:17]
	v_pk_fma_f32 v[46:47], v[6:7], v[46:47], v[14:15]
	v_pk_fma_f32 v[52:53], v[4:5], v[52:53], v[12:13]
	v_pk_fma_f32 v[50:51], v[2:3], v[50:51], v[10:11]
	v_pk_fma_f32 v[44:45], v[24:25], v[44:45], v[32:33]
	v_pk_fma_f32 v[42:43], v[22:23], v[42:43], v[30:31]
	v_pk_fma_f32 v[56:57], v[20:21], v[54:55], v[28:29]
	v_pk_fma_f32 v[54:55], v[18:19], v[66:67], v[26:27]
	s_and_b64 vcc, exec, s[20:21]
	s_cbranch_vccz .LBB0_1436
	s_xor_b32 s10, s0, 0xffff
	s_mov_b32 s11, 0
	s_lshl_b64 s[10:11], s[10:11], 12
	v_lshl_add_u64 v[64:65], v[62:63], 0, s[10:11]
	global_store_dwordx4 v[64:65], v[46:49], off nt
	global_store_dwordx4 v[64:65], v[50:53], off offset:16 nt
	global_store_dwordx4 v[64:65], v[42:45], off offset:2048 nt
	global_store_dwordx4 v[64:65], v[54:57], off offset:2064 nt
	s_cbranch_execz .LBB0_1437

.LBB0_1438:
	v_lshlrev_b32_e32 v42, 16, v38
	v_and_b32_e32 v43, 0xffff0000, v38
	v_lshlrev_b32_e32 v44, 16, v39
	v_and_b32_e32 v45, 0xffff0000, v39
	v_lshlrev_b32_e32 v39, 16, v35
	v_lshlrev_b32_e32 v38, 16, v34
	v_and_b32_e32 v35, 0xffff0000, v35
	v_and_b32_e32 v34, 0xffff0000, v34
	v_lshlrev_b32_e32 v46, 16, v40
	v_and_b32_e32 v48, 0xffff0000, v40
	v_lshlrev_b32_e32 v50, 16, v41
	v_and_b32_e32 v52, 0xffff0000, v41
	v_pk_add_f32 v[40:41], v[38:39], v[34:35]
	v_add_f32_e32 v47, v42, v43
	v_add_f32_e32 v0, v40, v41
	v_lshlrev_b32_e32 v41, 16, v37
	v_lshlrev_b32_e32 v40, 16, v36
	v_and_b32_e32 v37, 0xffff0000, v37
	v_and_b32_e32 v36, 0xffff0000, v36
	v_pk_add_f32 v[54:55], v[40:41], v[36:37]
	v_add_f32_e32 v53, 0, v0
	v_pk_add_f32 v[54:55], v[54:55], v[54:55] op_sel_hi:[0,1]
	v_add_f32_e32 v49, v44, v45
	v_mov_b32_e32 v51, v55
	v_pk_add_f32 v[56:57], v[46:47], v[48:49]
	v_pk_add_f32 v[54:55], v[50:51], v[52:53]
	s_mov_b64 s[6:7], -1
	v_pk_add_f32 v[54:55], v[56:57], v[54:55]
	s_nop 0
	v_add_f32_e32 v0, v54, v55
	ds_bpermute_b32 v47, v68, v0
	s_waitcnt lgkmcnt(0)
	v_add_f32_e32 v0, v0, v47
	ds_bpermute_b32 v47, v69, v0
	s_waitcnt lgkmcnt(0)
	v_add_f32_e32 v0, v0, v47
	ds_bpermute_b32 v47, v70, v0
	s_waitcnt lgkmcnt(0)
	v_add_f32_e32 v0, v0, v47
	ds_bpermute_b32 v47, v71, v0
	s_waitcnt lgkmcnt(0)
	v_add_f32_e32 v0, v0, v47
	ds_bpermute_b32 v47, v72, v0
	s_waitcnt lgkmcnt(0)
	v_add_f32_e32 v0, v0, v47
	ds_bpermute_b32 v47, v73, v0
	s_waitcnt lgkmcnt(0)
	v_add_f32_e32 v47, v0, v47
	v_fmac_f32_e32 v34, 0xba800000, v47
	v_fmac_f32_e32 v35, 0xba800000, v47
	v_fmac_f32_e32 v39, 0xba800000, v47
	v_fmac_f32_e32 v38, 0xba800000, v47
	v_mov_b32_e32 v54, v39
	v_mov_b32_e32 v55, v35
	v_mov_b32_e32 v39, v34
	v_pk_mul_f32 v[56:57], v[54:55], v[54:55]
	v_pk_mul_f32 v[34:35], v[38:39], v[38:39]
	v_fmac_f32_e32 v36, 0xba800000, v47
	v_fmac_f32_e32 v37, 0xba800000, v47
	v_fmac_f32_e32 v41, 0xba800000, v47
	v_pk_mov_b32 v[64:65], v[34:35], v[56:57] op_sel:[1,0]
	v_mov_b32_e32 v35, v57
	v_fmac_f32_e32 v40, 0xba800000, v47
	v_mov_b32_e32 v56, v41
	v_mov_b32_e32 v57, v37
	v_mov_b32_e32 v41, v36
	v_pk_add_f32 v[34:35], v[64:65], v[34:35]
	v_pk_mul_f32 v[64:65], v[56:57], v[56:57]
	v_pk_mul_f32 v[36:37], v[40:41], v[40:41]
	v_fmac_f32_e32 v42, 0xba800000, v47
	v_pk_mov_b32 v[66:67], v[36:37], v[64:65] op_sel:[1,0]
	v_mov_b32_e32 v37, v65
	v_fmac_f32_e32 v43, 0xba800000, v47
	v_fmac_f32_e32 v44, 0xba800000, v47
	v_mul_f32_e32 v0, v42, v42
	v_pk_add_f32 v[36:37], v[66:67], v[36:37]
	v_fmac_f32_e32 v45, 0xba800000, v47
	v_pk_fma_f32 v[64:65], v[42:43], v[42:43], v[0:1] op_sel_hi:[1,1,0]
	v_mul_f32_e32 v0, v44, v44
	v_pk_add_f32 v[34:35], v[34:35], v[34:35] op_sel_hi:[0,1]
	v_pk_add_f32 v[36:37], v[36:37], v[36:37] op_sel_hi:[0,1]
	v_pk_fma_f32 v[66:67], v[44:45], v[44:45], v[0:1] op_sel_hi:[1,1,0]
	v_fmac_f32_e32 v52, 0xba800000, v47
	v_fmac_f32_e32 v50, 0xba800000, v47
	v_fmac_f32_e32 v48, 0xba800000, v47
	v_fmac_f32_e32 v46, 0xba800000, v47
	v_mul_f32_e32 v64, v46, v46
	v_mul_f32_e32 v66, v48, v48
	v_mul_f32_e32 v34, v50, v50
	v_mul_f32_e32 v36, v52, v52
	v_pk_add_f32 v[64:65], v[64:65], v[66:67]
	v_pk_add_f32 v[34:35], v[34:35], v[36:37]
	v_mov_b32_e32 v47, v48
	v_pk_add_f32 v[34:35], v[64:65], v[34:35]
	v_mov_b32_e32 v51, v52
	v_add_f32_e32 v0, v34, v35
	ds_bpermute_b32 v34, v68, v0
	s_waitcnt lgkmcnt(0)
	v_add_f32_e32 v0, v0, v34
	ds_bpermute_b32 v34, v69, v0
	s_waitcnt lgkmcnt(0)
	v_add_f32_e32 v0, v0, v34
	ds_bpermute_b32 v34, v70, v0
	s_waitcnt lgkmcnt(0)
	v_add_f32_e32 v0, v0, v34
	ds_bpermute_b32 v34, v71, v0
	s_waitcnt lgkmcnt(0)
	v_add_f32_e32 v0, v0, v34
	ds_bpermute_b32 v34, v72, v0
	s_waitcnt lgkmcnt(0)
	v_add_f32_e32 v0, v0, v34
	ds_bpermute_b32 v34, v73, v0
	s_waitcnt lgkmcnt(0)
	v_add_f32_e32 v0, v0, v34
	v_fmamk_f32 v0, v0, 0x3a800000, v227
	v_mul_f32_e32 v34, 0x4b800000, v0
	v_cmp_gt_f32_e32 vcc, s86, v0
	s_nop 1
	v_cndmask_b32_e32 v0, v0, v34, vcc
	v_rsq_f32_e32 v0, v0
	s_nop 0
	v_mul_f32_e32 v34, 0x45800000, v0
	v_cndmask_b32_e32 v0, v0, v34, vcc
	v_pk_mul_f32 v[34:35], v[38:39], v[0:1] op_sel_hi:[1,0]
	v_pk_mul_f32 v[36:37], v[54:55], v[0:1] op_sel_hi:[1,0]
	v_pk_mul_f32 v[38:39], v[40:41], v[0:1] op_sel_hi:[1,0]
	v_pk_mul_f32 v[40:41], v[56:57], v[0:1] op_sel_hi:[1,0]
	v_pk_mul_f32 v[42:43], v[42:43], v[0:1] op_sel_hi:[1,0]
	v_pk_mul_f32 v[44:45], v[44:45], v[0:1] op_sel_hi:[1,0]
	v_pk_mul_f32 v[46:47], v[46:47], v[0:1] op_sel_hi:[1,0]
	v_pk_mul_f32 v[48:49], v[50:51], v[0:1] op_sel_hi:[1,0]
	v_pk_fma_f32 v[36:37], v[8:9], v[36:37], v[16:17]
	v_pk_fma_f32 v[34:35], v[6:7], v[34:35], v[14:15]
	v_pk_fma_f32 v[40:41], v[4:5], v[40:41], v[12:13]
	v_pk_fma_f32 v[38:39], v[2:3], v[38:39], v[10:11]
	v_pk_fma_f32 v[44:45], v[24:25], v[44:45], v[32:33]
	v_pk_fma_f32 v[42:43], v[22:23], v[42:43], v[30:31]
	v_pk_fma_f32 v[48:49], v[20:21], v[48:49], v[28:29]
	v_pk_fma_f32 v[46:47], v[18:19], v[46:47], v[26:27]
	s_andn2_b64 vcc, exec, s[20:21]
	s_cbranch_vccnz .LBB0_1440
	s_xor_b32 s4, s4, 0xffff
	s_mov_b32 s5, 0
	s_lshl_b64 s[6:7], s[4:5], 12
	v_lshl_add_u64 v[50:51], v[62:63], 0, s[6:7]
	s_mov_b64 s[6:7], 0
	global_store_dwordx4 v[50:51], v[34:37], off nt
	global_store_dwordx4 v[50:51], v[38:41], off offset:16 nt
	global_store_dwordx4 v[50:51], v[42:45], off offset:2048 nt
	global_store_dwordx4 v[50:51], v[46:49], off offset:2064 nt
